# write-through (sc1) on full-line dwordx4 stores that are consumed cross-XCD: SwiGLU ACT tile, converted bf16 weights, H tiles of the fused epilogues
# speedup vs baseline: 1.0062x; 1.0062x over previous
.LBB0_114:
	v_mad_i64_i32 v[30:31], s[30:31], s30, v31, 0
	v_lshl_add_u64 v[8:9], v[30:31], 1, v[8:9]
	global_store_dwordx4 v[8:9], v[0:3], off sc1
	s_waitcnt lgkmcnt(0)
	s_add_i32 s44, s44, s33
	s_cmpk_lt_i32 s44, 0x1580
	s_cbranch_scc0 .LBB0_151

.LBB0_128:
	s_lshl_b64 s[38:39], s[38:39], 1
	s_add_u32 s36, s36, s38
	s_addc_u32 s37, s37, s39
	v_lshl_add_u64 v[8:9], s[36:37], 0, v[6:7]
	v_mad_i64_i32 v[34:35], s[36:37], s30, v31, 0
	v_lshl_add_u64 v[34:35], v[34:35], 1, v[8:9]
	ds_read2_b32 v[32:33], v13 offset0:8 offset1:41
	global_store_dwordx4 v[34:35], v[0:3], off sc1
	s_cmp_gt_i32 s45, 1
	s_mov_b64 s[36:37], -1
	s_waitcnt lgkmcnt(0)
	v_cvt_pk_bf16_f32 v0, v32, v33
	ds_read2_b32 v[2:3], v13 offset0:74 offset1:107
	s_waitcnt lgkmcnt(0)
	v_cvt_pk_bf16_f32 v1, v2, v3
	ds_read2_b32 v[2:3], v13 offset0:140 offset1:173
	s_waitcnt lgkmcnt(0)
	v_cvt_pk_bf16_f32 v2, v2, v3
	ds_read2_b32 v[32:33], v13 offset0:206 offset1:239
	s_waitcnt lgkmcnt(0)
	v_cvt_pk_bf16_f32 v3, v32, v33
	s_cbranch_scc0 .LBB0_130
	v_or_b32_e32 v31, v30, v16
	s_mov_b64 s[36:37], 0

.LBB0_135:
	v_mad_i64_i32 v[34:35], s[36:37], s30, v31, 0
	v_lshl_add_u64 v[34:35], v[34:35], 1, v[8:9]
	ds_read2_b32 v[32:33], v13 offset0:16 offset1:49
	global_store_dwordx4 v[34:35], v[0:3], off sc1
	s_cmp_gt_i32 s45, 1
	s_mov_b64 s[36:37], -1
	s_waitcnt lgkmcnt(0)
	v_cvt_pk_bf16_f32 v0, v32, v33
	ds_read2_b32 v[2:3], v13 offset0:82 offset1:115
	s_waitcnt lgkmcnt(0)
	v_cvt_pk_bf16_f32 v1, v2, v3
	ds_read2_b32 v[2:3], v13 offset0:148 offset1:181
	s_waitcnt lgkmcnt(0)
	v_cvt_pk_bf16_f32 v2, v2, v3
	ds_read2_b32 v[32:33], v13 offset0:214 offset1:247
	s_waitcnt lgkmcnt(0)
	v_cvt_pk_bf16_f32 v3, v32, v33
	s_cbranch_scc0 .LBB0_137
	v_or_b32_e32 v31, v30, v18
	s_mov_b64 s[36:37], 0

.LBB0_142:
	v_mad_i64_i32 v[34:35], s[36:37], s30, v31, 0
	v_lshl_add_u64 v[34:35], v[34:35], 1, v[8:9]
	ds_read2_b32 v[32:33], v13 offset0:24 offset1:57
	global_store_dwordx4 v[34:35], v[0:3], off sc1
	s_cmp_gt_i32 s45, 1
	s_mov_b64 s[36:37], -1
	s_waitcnt lgkmcnt(0)
	v_cvt_pk_bf16_f32 v0, v32, v33
	ds_read2_b32 v[2:3], v13 offset0:90 offset1:123
	s_waitcnt lgkmcnt(0)
	v_cvt_pk_bf16_f32 v1, v2, v3
	ds_read2_b32 v[2:3], v13 offset0:156 offset1:189
	s_waitcnt lgkmcnt(0)
	v_cvt_pk_bf16_f32 v2, v2, v3
	ds_read2_b32 v[32:33], v13 offset0:222 offset1:255
	s_waitcnt lgkmcnt(0)
	v_cvt_pk_bf16_f32 v3, v32, v33
	s_cbranch_scc0 .LBB0_144
	v_or_b32_e32 v31, v30, v20
	s_mov_b64 s[36:37], 0

.LBB0_646:
	s_and_saveexec_b64 s[4:5], s[2:3]
	v_rsq_f32_e32 v98, v166
	ds_write_b32 v99, v98 offset:4096
	s_or_b64 exec, exec, s[4:5]
	s_waitcnt lgkmcnt(0)
	s_barrier
	s_add_i32 s24, s24, s25
	v_lshl_add_u32 v170, v238, 2, s20
	v_lshl_add_u32 v98, v96, 3, s26
	ds_read_b32 v96, v170 offset:4096
	v_ashrrev_i32_e32 v99, 31, v98
	v_add_u32_e32 v164, s24, v238
	v_lshl_add_u64 v[98:99], v[98:99], 1, s[16:17]
	s_mov_b64 s[2:3], 0x5000000
	v_ashrrev_i32_e32 v165, 31, v164
	v_lshl_add_u64 v[98:99], v[98:99], 0, s[2:3]
	v_lshlrev_b64 v[166:167], 11, v[164:165]
	s_waitcnt lgkmcnt(0)
	v_pk_mul_f32 v[128:129], v[128:129], v[96:97] op_sel_hi:[1,0]
	v_pk_mul_f32 v[130:131], v[130:131], v[96:97] op_sel_hi:[1,0]
	v_pk_mul_f32 v[124:125], v[124:125], v[96:97] op_sel_hi:[1,0]
	v_pk_mul_f32 v[126:127], v[126:127], v[96:97] op_sel_hi:[1,0]
	v_pk_mul_f32 v[118:119], v[118:119], v[96:97] op_sel_hi:[1,0]
	v_lshl_add_u64 v[166:167], v[98:99], 0, v[166:167]
	s_waitcnt vmcnt(20)
	v_pk_fma_f32 v[128:129], v[14:15], v[128:129], v[30:31]
	v_pk_fma_f32 v[130:131], v[12:13], v[130:131], v[28:29]
	v_pk_fma_f32 v[126:127], v[4:5], v[126:127], v[20:21]
	v_pk_fma_f32 v[168:169], v[6:7], v[124:125], v[22:23]
	v_cvt_pk_bf16_f32 v124, v130, v131
	v_cvt_pk_bf16_f32 v125, v128, v129
	v_pk_mul_f32 v[120:121], v[120:121], v[96:97] op_sel_hi:[1,0]
	v_pk_mul_f32 v[122:123], v[122:123], v[96:97] op_sel_hi:[1,0]
	v_pk_mul_f32 v[116:117], v[116:117], v[96:97] op_sel_hi:[1,0]
	s_waitcnt vmcnt(17)
	v_pk_fma_f32 v[118:119], v[0:1], v[118:119], v[16:17]
	v_cvt_pk_bf16_f32 v126, v126, v127
	v_cvt_pk_bf16_f32 v127, v168, v169
	global_store_dwordx4 v[166:167], v[124:127], off sc1
	s_waitcnt vmcnt(17)
	v_pk_fma_f32 v[120:121], v[10:11], v[120:121], v[26:27]
	v_pk_fma_f32 v[122:123], v[8:9], v[122:123], v[24:25]
	v_pk_fma_f32 v[124:125], v[2:3], v[116:117], v[18:19]
	v_cvt_pk_bf16_f32 v116, v122, v123
	v_cvt_pk_bf16_f32 v117, v120, v121
	v_cvt_pk_bf16_f32 v118, v118, v119
	s_nop 0
	v_cvt_pk_bf16_f32 v119, v124, v125
	global_store_dwordx4 v[166:167], v[116:119], off offset:256 sc1
	ds_read_b32 v96, v170 offset:4160
	s_waitcnt lgkmcnt(0)
	v_pk_mul_f32 v[112:113], v[112:113], v[96:97] op_sel_hi:[1,0]
	v_add_u32_e32 v116, 16, v164
	v_ashrrev_i32_e32 v117, 31, v116
	v_lshlrev_b64 v[116:117], 11, v[116:117]
	v_pk_mul_f32 v[114:115], v[114:115], v[96:97] op_sel_hi:[1,0]
	v_pk_mul_f32 v[108:109], v[108:109], v[96:97] op_sel_hi:[1,0]
	v_pk_mul_f32 v[110:111], v[110:111], v[96:97] op_sel_hi:[1,0]
	v_pk_mul_f32 v[102:103], v[102:103], v[96:97] op_sel_hi:[1,0]
	v_lshl_add_u64 v[116:117], v[98:99], 0, v[116:117]
	v_pk_fma_f32 v[112:113], v[14:15], v[112:113], v[30:31]
	v_pk_fma_f32 v[114:115], v[12:13], v[114:115], v[28:29]
	v_pk_fma_f32 v[110:111], v[4:5], v[110:111], v[20:21]
	v_pk_fma_f32 v[118:119], v[6:7], v[108:109], v[22:23]
	v_cvt_pk_bf16_f32 v108, v114, v115
	v_cvt_pk_bf16_f32 v109, v112, v113
	v_pk_mul_f32 v[104:105], v[104:105], v[96:97] op_sel_hi:[1,0]
	v_pk_mul_f32 v[106:107], v[106:107], v[96:97] op_sel_hi:[1,0]
	v_pk_mul_f32 v[100:101], v[100:101], v[96:97] op_sel_hi:[1,0]
	v_pk_fma_f32 v[102:103], v[0:1], v[102:103], v[16:17]
	v_cvt_pk_bf16_f32 v110, v110, v111
	v_cvt_pk_bf16_f32 v111, v118, v119
	global_store_dwordx4 v[116:117], v[108:111], off sc1
	v_pk_fma_f32 v[104:105], v[10:11], v[104:105], v[26:27]
	v_pk_fma_f32 v[106:107], v[8:9], v[106:107], v[24:25]
	v_pk_fma_f32 v[108:109], v[2:3], v[100:101], v[18:19]
	v_cvt_pk_bf16_f32 v100, v106, v107
	v_cvt_pk_bf16_f32 v101, v104, v105
	v_cvt_pk_bf16_f32 v102, v102, v103
	s_nop 0
	v_cvt_pk_bf16_f32 v103, v108, v109
	global_store_dwordx4 v[116:117], v[100:103], off offset:256 sc1
	ds_read_b32 v96, v170 offset:4224
	s_waitcnt lgkmcnt(0)
	v_pk_mul_f32 v[92:93], v[92:93], v[96:97] op_sel_hi:[1,0]
	v_add_u32_e32 v100, 32, v164
	v_ashrrev_i32_e32 v101, 31, v100
	v_lshlrev_b64 v[100:101], 11, v[100:101]
	v_pk_mul_f32 v[94:95], v[94:95], v[96:97] op_sel_hi:[1,0]
	v_pk_mul_f32 v[88:89], v[88:89], v[96:97] op_sel_hi:[1,0]
	v_pk_mul_f32 v[90:91], v[90:91], v[96:97] op_sel_hi:[1,0]
	v_pk_mul_f32 v[82:83], v[82:83], v[96:97] op_sel_hi:[1,0]
	v_lshl_add_u64 v[100:101], v[98:99], 0, v[100:101]
	v_pk_fma_f32 v[92:93], v[14:15], v[92:93], v[30:31]
	v_pk_fma_f32 v[94:95], v[12:13], v[94:95], v[28:29]
	v_pk_fma_f32 v[90:91], v[4:5], v[90:91], v[20:21]
	v_pk_fma_f32 v[102:103], v[6:7], v[88:89], v[22:23]
	v_cvt_pk_bf16_f32 v88, v94, v95
	v_cvt_pk_bf16_f32 v89, v92, v93
	v_pk_mul_f32 v[84:85], v[84:85], v[96:97] op_sel_hi:[1,0]
	v_pk_mul_f32 v[86:87], v[86:87], v[96:97] op_sel_hi:[1,0]
	v_pk_mul_f32 v[80:81], v[80:81], v[96:97] op_sel_hi:[1,0]
	v_pk_fma_f32 v[82:83], v[0:1], v[82:83], v[16:17]
	v_cvt_pk_bf16_f32 v90, v90, v91
	v_cvt_pk_bf16_f32 v91, v102, v103
	global_store_dwordx4 v[100:101], v[88:91], off sc1
	v_pk_fma_f32 v[84:85], v[10:11], v[84:85], v[26:27]
	v_pk_fma_f32 v[86:87], v[8:9], v[86:87], v[24:25]
	v_pk_fma_f32 v[88:89], v[2:3], v[80:81], v[18:19]
	v_cvt_pk_bf16_f32 v80, v86, v87
	v_cvt_pk_bf16_f32 v81, v84, v85
	v_cvt_pk_bf16_f32 v82, v82, v83
	s_nop 0
	v_cvt_pk_bf16_f32 v83, v88, v89
	global_store_dwordx4 v[100:101], v[80:83], off offset:256 sc1
	ds_read_b32 v80, v170 offset:4288
	s_waitcnt lgkmcnt(0)
	v_pk_mul_f32 v[76:77], v[76:77], v[80:81] op_sel_hi:[1,0]
	v_add_u32_e32 v82, 48, v164
	v_ashrrev_i32_e32 v83, 31, v82
	v_lshlrev_b64 v[82:83], 11, v[82:83]
	v_pk_mul_f32 v[78:79], v[78:79], v[80:81] op_sel_hi:[1,0]
	v_pk_mul_f32 v[72:73], v[72:73], v[80:81] op_sel_hi:[1,0]
	v_pk_mul_f32 v[74:75], v[74:75], v[80:81] op_sel_hi:[1,0]
	v_pk_mul_f32 v[66:67], v[66:67], v[80:81] op_sel_hi:[1,0]
	v_lshl_add_u64 v[82:83], v[98:99], 0, v[82:83]
	v_pk_fma_f32 v[76:77], v[14:15], v[76:77], v[30:31]
	v_pk_fma_f32 v[78:79], v[12:13], v[78:79], v[28:29]
	v_pk_fma_f32 v[74:75], v[4:5], v[74:75], v[20:21]
	v_pk_fma_f32 v[84:85], v[6:7], v[72:73], v[22:23]
	v_cvt_pk_bf16_f32 v72, v78, v79
	v_cvt_pk_bf16_f32 v73, v76, v77
	v_pk_mul_f32 v[68:69], v[68:69], v[80:81] op_sel_hi:[1,0]
	v_pk_mul_f32 v[70:71], v[70:71], v[80:81] op_sel_hi:[1,0]
	v_pk_mul_f32 v[64:65], v[64:65], v[80:81] op_sel_hi:[1,0]
	v_pk_fma_f32 v[66:67], v[0:1], v[66:67], v[16:17]
	v_cvt_pk_bf16_f32 v74, v74, v75
	v_cvt_pk_bf16_f32 v75, v84, v85
	global_store_dwordx4 v[82:83], v[72:75], off sc1
	v_pk_fma_f32 v[68:69], v[10:11], v[68:69], v[26:27]
	v_pk_fma_f32 v[70:71], v[8:9], v[70:71], v[24:25]
	v_pk_fma_f32 v[72:73], v[2:3], v[64:65], v[18:19]
	v_cvt_pk_bf16_f32 v64, v70, v71
	v_cvt_pk_bf16_f32 v65, v68, v69
	v_cvt_pk_bf16_f32 v66, v66, v67
	s_nop 0
	v_cvt_pk_bf16_f32 v67, v72, v73
	global_store_dwordx4 v[82:83], v[64:67], off offset:256 sc1
	ds_read_b32 v64, v170 offset:4608
	s_waitcnt lgkmcnt(0)
	v_pk_mul_f32 v[60:61], v[60:61], v[64:65] op_sel_hi:[1,0]
	v_add_u32_e32 v66, 0x80, v164
	v_ashrrev_i32_e32 v67, 31, v66
	v_lshlrev_b64 v[66:67], 11, v[66:67]
	v_pk_mul_f32 v[62:63], v[62:63], v[64:65] op_sel_hi:[1,0]
	v_pk_mul_f32 v[56:57], v[56:57], v[64:65] op_sel_hi:[1,0]
	v_pk_mul_f32 v[58:59], v[58:59], v[64:65] op_sel_hi:[1,0]
	v_pk_mul_f32 v[50:51], v[50:51], v[64:65] op_sel_hi:[1,0]
	v_lshl_add_u64 v[66:67], v[98:99], 0, v[66:67]
	v_pk_fma_f32 v[60:61], v[14:15], v[60:61], v[30:31]
	v_pk_fma_f32 v[62:63], v[12:13], v[62:63], v[28:29]
	v_pk_fma_f32 v[58:59], v[4:5], v[58:59], v[20:21]
	v_pk_fma_f32 v[68:69], v[6:7], v[56:57], v[22:23]
	v_cvt_pk_bf16_f32 v56, v62, v63
	v_cvt_pk_bf16_f32 v57, v60, v61
	v_pk_mul_f32 v[52:53], v[52:53], v[64:65] op_sel_hi:[1,0]
	v_pk_mul_f32 v[54:55], v[54:55], v[64:65] op_sel_hi:[1,0]
	v_pk_mul_f32 v[48:49], v[48:49], v[64:65] op_sel_hi:[1,0]
	v_pk_fma_f32 v[50:51], v[0:1], v[50:51], v[16:17]
	v_cvt_pk_bf16_f32 v58, v58, v59
	v_cvt_pk_bf16_f32 v59, v68, v69
	global_store_dwordx4 v[66:67], v[56:59], off sc1
	v_pk_fma_f32 v[52:53], v[10:11], v[52:53], v[26:27]
	v_pk_fma_f32 v[54:55], v[8:9], v[54:55], v[24:25]
	v_pk_fma_f32 v[56:57], v[2:3], v[48:49], v[18:19]
	v_cvt_pk_bf16_f32 v48, v54, v55
	v_cvt_pk_bf16_f32 v49, v52, v53
	v_cvt_pk_bf16_f32 v50, v50, v51
	s_nop 0
	v_cvt_pk_bf16_f32 v51, v56, v57
	global_store_dwordx4 v[66:67], v[48:51], off offset:256 sc1
	ds_read_b32 v48, v170 offset:4672
	s_waitcnt lgkmcnt(0)
	v_pk_mul_f32 v[44:45], v[44:45], v[48:49] op_sel_hi:[1,0]
	v_add_u32_e32 v50, 0x90, v164
	v_ashrrev_i32_e32 v51, 31, v50
	v_lshlrev_b64 v[50:51], 11, v[50:51]
	v_pk_mul_f32 v[46:47], v[46:47], v[48:49] op_sel_hi:[1,0]
	v_pk_mul_f32 v[40:41], v[40:41], v[48:49] op_sel_hi:[1,0]
	v_pk_mul_f32 v[42:43], v[42:43], v[48:49] op_sel_hi:[1,0]
	v_pk_mul_f32 v[34:35], v[34:35], v[48:49] op_sel_hi:[1,0]
	v_lshl_add_u64 v[50:51], v[98:99], 0, v[50:51]
	v_pk_fma_f32 v[44:45], v[14:15], v[44:45], v[30:31]
	v_pk_fma_f32 v[46:47], v[12:13], v[46:47], v[28:29]
	v_pk_fma_f32 v[42:43], v[4:5], v[42:43], v[20:21]
	v_pk_fma_f32 v[52:53], v[6:7], v[40:41], v[22:23]
	v_cvt_pk_bf16_f32 v40, v46, v47
	v_cvt_pk_bf16_f32 v41, v44, v45
	v_pk_mul_f32 v[36:37], v[36:37], v[48:49] op_sel_hi:[1,0]
	v_pk_mul_f32 v[38:39], v[38:39], v[48:49] op_sel_hi:[1,0]
	v_pk_mul_f32 v[32:33], v[32:33], v[48:49] op_sel_hi:[1,0]
	v_pk_fma_f32 v[34:35], v[0:1], v[34:35], v[16:17]
	v_cvt_pk_bf16_f32 v42, v42, v43
	v_cvt_pk_bf16_f32 v43, v52, v53
	global_store_dwordx4 v[50:51], v[40:43], off sc1
	v_pk_fma_f32 v[36:37], v[10:11], v[36:37], v[26:27]
	v_pk_fma_f32 v[38:39], v[8:9], v[38:39], v[24:25]
	v_pk_fma_f32 v[40:41], v[2:3], v[32:33], v[18:19]
	v_cvt_pk_bf16_f32 v32, v38, v39
	v_cvt_pk_bf16_f32 v33, v36, v37
	v_cvt_pk_bf16_f32 v34, v34, v35
	s_nop 0
	v_cvt_pk_bf16_f32 v35, v40, v41
	global_store_dwordx4 v[50:51], v[32:35], off offset:256 sc1
	ds_read_b32 v36, v170 offset:4736
	s_waitcnt lgkmcnt(0)
	v_pk_mul_f32 v[42:43], v[142:143], v[36:37] op_sel_hi:[1,0]
	v_add_u32_e32 v32, 0xa0, v164
	v_ashrrev_i32_e32 v33, 31, v32
	v_lshlrev_b64 v[32:33], 11, v[32:33]
	v_lshl_add_u64 v[38:39], v[98:99], 0, v[32:33]
	v_pk_mul_f32 v[32:33], v[132:133], v[36:37] op_sel_hi:[1,0]
	v_pk_mul_f32 v[34:35], v[134:135], v[36:37] op_sel_hi:[1,0]
	v_pk_fma_f32 v[40:41], v[14:15], v[32:33], v[30:31]
	v_pk_fma_f32 v[32:33], v[12:13], v[34:35], v[28:29]
	v_pk_mul_f32 v[34:35], v[140:141], v[36:37] op_sel_hi:[1,0]
	v_pk_fma_f32 v[42:43], v[4:5], v[42:43], v[20:21]
	v_pk_fma_f32 v[44:45], v[6:7], v[34:35], v[22:23]
	v_cvt_pk_bf16_f32 v32, v32, v33
	v_cvt_pk_bf16_f32 v33, v40, v41
	v_cvt_pk_bf16_f32 v34, v42, v43
	s_nop 0
	v_cvt_pk_bf16_f32 v35, v44, v45
	global_store_dwordx4 v[38:39], v[32:35], off sc1
	s_nop 1
	v_pk_mul_f32 v[32:33], v[136:137], v[36:37] op_sel_hi:[1,0]
	v_pk_mul_f32 v[34:35], v[138:139], v[36:37] op_sel_hi:[1,0]
	v_pk_fma_f32 v[40:41], v[10:11], v[32:33], v[26:27]
	v_pk_fma_f32 v[32:33], v[8:9], v[34:35], v[24:25]
	v_pk_mul_f32 v[34:35], v[144:145], v[36:37] op_sel_hi:[1,0]
	v_pk_mul_f32 v[36:37], v[146:147], v[36:37] op_sel_hi:[1,0]
	v_pk_fma_f32 v[42:43], v[2:3], v[34:35], v[18:19]
	v_pk_fma_f32 v[36:37], v[0:1], v[36:37], v[16:17]
	v_cvt_pk_bf16_f32 v32, v32, v33
	v_cvt_pk_bf16_f32 v33, v40, v41
	s_nop 0
	v_cvt_pk_bf16_f32 v34, v36, v37
	v_cvt_pk_bf16_f32 v35, v42, v43
	global_store_dwordx4 v[38:39], v[32:35], off offset:256 sc1
	ds_read_b32 v32, v170 offset:4800
	s_waitcnt lgkmcnt(0)
	v_pk_mul_f32 v[36:37], v[150:151], v[32:33] op_sel_hi:[1,0]
	v_add_u32_e32 v34, 0xb0, v164
	v_ashrrev_i32_e32 v35, 31, v34
	v_pk_mul_f32 v[38:39], v[154:155], v[32:33] op_sel_hi:[1,0]
	v_lshlrev_b64 v[34:35], 11, v[34:35]
	v_pk_fma_f32 v[14:15], v[14:15], v[36:37], v[30:31]
	v_pk_fma_f32 v[12:13], v[12:13], v[38:39], v[28:29]
	v_pk_mul_f32 v[28:29], v[158:159], v[32:33] op_sel_hi:[1,0]
	v_pk_mul_f32 v[30:31], v[162:163], v[32:33] op_sel_hi:[1,0]
	v_lshl_add_u64 v[34:35], v[98:99], 0, v[34:35]
	v_pk_fma_f32 v[20:21], v[4:5], v[30:31], v[20:21]
	v_pk_fma_f32 v[22:23], v[6:7], v[28:29], v[22:23]
	v_cvt_pk_bf16_f32 v4, v12, v13
	v_cvt_pk_bf16_f32 v5, v14, v15
	v_cvt_pk_bf16_f32 v6, v20, v21
	s_nop 0
	v_cvt_pk_bf16_f32 v7, v22, v23
	global_store_dwordx4 v[34:35], v[4:7], off sc1
	s_nop 1
	v_pk_mul_f32 v[4:5], v[148:149], v[32:33] op_sel_hi:[1,0]
	v_pk_mul_f32 v[6:7], v[152:153], v[32:33] op_sel_hi:[1,0]
	v_pk_fma_f32 v[4:5], v[10:11], v[4:5], v[26:27]
	v_pk_fma_f32 v[6:7], v[8:9], v[6:7], v[24:25]
	v_pk_mul_f32 v[8:9], v[156:157], v[32:33] op_sel_hi:[1,0]
	v_pk_mul_f32 v[10:11], v[160:161], v[32:33] op_sel_hi:[1,0]
	v_pk_fma_f32 v[8:9], v[2:3], v[8:9], v[18:19]
	v_pk_fma_f32 v[10:11], v[0:1], v[10:11], v[16:17]
	v_cvt_pk_bf16_f32 v0, v6, v7
	v_cvt_pk_bf16_f32 v1, v4, v5
	s_nop 0
	v_cvt_pk_bf16_f32 v2, v10, v11
	v_cvt_pk_bf16_f32 v3, v8, v9
	global_store_dwordx4 v[34:35], v[0:3], off offset:256 sc1

.LBB0_736:
	v_mov_b32_e32 v140, v145
	s_mov_b32 s17, s79
	v_mov_b32_e32 v141, v144
	s_mov_b32 s19, s62
	s_lshl_b32 s24, s24, 8
	s_lshl_b32 s19, s19, 6
	s_add_i32 s19, s19, s24
	v_add_u32_e32 v148, s19, v141
	s_lshl_b32 s19, s25, 7
	s_lshl_b32 s17, s17, 4
	s_add_i32 s17, s17, s19
	v_lshl_add_u32 v142, v140, 2, s17
	v_ashrrev_i32_e32 v143, 31, v142
	v_mov_b64_e32 v[140:141], s[6:7]
	v_mad_i64_i32 v[150:151], s[24:25], v148, s47, v[140:141]
	v_lshlrev_b64 v[142:143], 1, v[142:143]
	v_lshl_add_u64 v[150:151], v[150:151], 0, v[142:143]
	s_andn2_b64 vcc, exec, s[2:3]
	v_mul_f32_e32 v152, 0xbfb8aa3b, v126
	v_mul_f32_e32 v153, 0xbfb8aa3b, v127
	v_mul_f32_e32 v154, 0xbfb8aa3b, v128
	v_mul_f32_e32 v155, 0xbfb8aa3b, v129
	v_mul_f32_e32 v156, 0xbfb8aa3b, v118
	v_mul_f32_e32 v157, 0xbfb8aa3b, v119
	v_mul_f32_e32 v158, 0xbfb8aa3b, v120
	v_mul_f32_e32 v159, 0xbfb8aa3b, v121
	v_exp_f32_e32 v152, v152
	v_exp_f32_e32 v153, v153
	v_exp_f32_e32 v154, v154
	v_exp_f32_e32 v155, v155
	v_exp_f32_e32 v156, v156
	v_exp_f32_e32 v157, v157
	v_exp_f32_e32 v158, v158
	v_exp_f32_e32 v159, v159
	v_add_f32_e32 v152, 1.0, v152
	v_add_f32_e32 v153, 1.0, v153
	v_add_f32_e32 v154, 1.0, v154
	v_add_f32_e32 v155, 1.0, v155
	v_add_f32_e32 v156, 1.0, v156
	v_add_f32_e32 v157, 1.0, v157
	v_add_f32_e32 v158, 1.0, v158
	v_add_f32_e32 v159, 1.0, v159
	v_rcp_f32_e32 v152, v152
	v_rcp_f32_e32 v153, v153
	v_rcp_f32_e32 v154, v154
	v_rcp_f32_e32 v155, v155
	v_rcp_f32_e32 v156, v156
	v_rcp_f32_e32 v157, v157
	v_rcp_f32_e32 v158, v158
	v_rcp_f32_e32 v159, v159
	v_mul_f32_e32 v152, v126, v152
	v_mul_f32_e32 v153, v127, v153
	v_mul_f32_e32 v154, v128, v154
	v_mul_f32_e32 v155, v129, v155
	v_mul_f32_e32 v156, v118, v156
	v_mul_f32_e32 v157, v119, v157
	v_mul_f32_e32 v158, v120, v158
	v_mul_f32_e32 v159, v121, v159
	v_mul_f32_e32 v122, v122, v152
	v_mul_f32_e32 v123, v123, v153
	v_mul_f32_e32 v124, v124, v154
	v_mul_f32_e32 v125, v125, v155
	v_mul_f32_e32 v114, v114, v156
	v_mul_f32_e32 v115, v115, v157
	v_mul_f32_e32 v116, v116, v158
	v_mul_f32_e32 v117, v117, v159
	v_cvt_pk_bf16_f32 v122, v122, v123
	v_cvt_pk_bf16_f32 v123, v124, v125
	v_cvt_pk_bf16_f32 v114, v114, v115
	v_cvt_pk_bf16_f32 v115, v116, v117
	v_mul_f32_e32 v152, 0xbfb8aa3b, v110
	v_mul_f32_e32 v153, 0xbfb8aa3b, v111
	v_mul_f32_e32 v154, 0xbfb8aa3b, v112
	v_mul_f32_e32 v155, 0xbfb8aa3b, v113
	v_mul_f32_e32 v156, 0xbfb8aa3b, v102
	v_mul_f32_e32 v157, 0xbfb8aa3b, v103
	v_mul_f32_e32 v158, 0xbfb8aa3b, v104
	v_mul_f32_e32 v159, 0xbfb8aa3b, v105
	v_exp_f32_e32 v152, v152
	v_exp_f32_e32 v153, v153
	v_exp_f32_e32 v154, v154
	v_exp_f32_e32 v155, v155
	v_exp_f32_e32 v156, v156
	v_exp_f32_e32 v157, v157
	v_exp_f32_e32 v158, v158
	v_exp_f32_e32 v159, v159
	v_add_f32_e32 v152, 1.0, v152
	v_add_f32_e32 v153, 1.0, v153
	v_add_f32_e32 v154, 1.0, v154
	v_add_f32_e32 v155, 1.0, v155
	v_add_f32_e32 v156, 1.0, v156
	v_add_f32_e32 v157, 1.0, v157
	v_add_f32_e32 v158, 1.0, v158
	v_add_f32_e32 v159, 1.0, v159
	v_rcp_f32_e32 v152, v152
	v_rcp_f32_e32 v153, v153
	v_rcp_f32_e32 v154, v154
	v_rcp_f32_e32 v155, v155
	v_rcp_f32_e32 v156, v156
	v_rcp_f32_e32 v157, v157
	v_rcp_f32_e32 v158, v158
	v_rcp_f32_e32 v159, v159
	v_mul_f32_e32 v152, v110, v152
	v_mul_f32_e32 v153, v111, v153
	v_mul_f32_e32 v154, v112, v154
	v_mul_f32_e32 v155, v113, v155
	v_mul_f32_e32 v156, v102, v156
	v_mul_f32_e32 v157, v103, v157
	v_mul_f32_e32 v158, v104, v158
	v_mul_f32_e32 v159, v105, v159
	v_mul_f32_e32 v106, v106, v152
	v_mul_f32_e32 v107, v107, v153
	v_mul_f32_e32 v108, v108, v154
	v_mul_f32_e32 v109, v109, v155
	v_mul_f32_e32 v98, v98, v156
	v_mul_f32_e32 v99, v99, v157
	v_mul_f32_e32 v100, v100, v158
	v_mul_f32_e32 v101, v101, v159
	v_cvt_pk_bf16_f32 v106, v106, v107
	v_cvt_pk_bf16_f32 v107, v108, v109
	v_cvt_pk_bf16_f32 v98, v98, v99
	v_cvt_pk_bf16_f32 v99, v100, v101
	v_and_b32_e32 v160, 7, v144
	v_lshlrev_b32_e32 v160, 1, v160
	s_lshl_b32 s100, s79, 2
	v_add_u32_e32 v161, s100, v145
	v_xor_b32_e32 v161, v161, v160
	v_lshlrev_b32_e32 v161, 3, v161
	v_lshl_add_u32 v161, v144, 8, v161
	s_lshl_b32 s100, s62, 13
	s_add_i32 s100, s100, 49152
	v_add_u32_e32 v161, s100, v161
	v_add_u32_e32 v167, 98304, v161
	v_xor_b32_e32 v162, v144, v145
	v_lshlrev_b32_e32 v162, 4, v162
	s_lshl_b32 s101, s79, 11
	s_add_i32 s101, s101, s100
	v_lshl_add_u32 v163, v145, 8, s101
	v_add_u32_e32 v164, v163, v162
	v_or_b32_e32 v165, 4, v145
	v_xor_b32_e32 v165, v144, v165
	v_lshl_add_u32 v165, v165, 4, v163
	v_add_u32_e32 v174, 98304, v164
	v_add_u32_e32 v175, 98304, v165
	v_sub_u32_e32 v166, v148, v144
	s_lshl_b32 s101, s79, 3
	v_add3_u32 v166, v166, s101, v145
	v_mov_b64_e32 v[170:171], s[6:7]
	v_mad_u64_u32 v[168:169], s[24:25], v166, s47, v[170:171]
	s_lshl_b32 s101, s79, 5
	v_subrev_u32_e32 v172, s101, v142
	v_lshlrev_b32_e32 v173, 3, v145
	v_sub_u32_e32 v172, v172, v173
	v_lshl_add_u32 v172, v144, 4, v172
	v_mov_b32_e32 v173, 0
	v_lshl_add_u64 v[168:169], v[168:169], 0, v[172:173]
	s_mov_b32 s101, 0
	ds_write_b64 v161, v[122:123] offset:0
	ds_write_b64 v161, v[114:115] offset:128
	ds_write_b64 v161, v[106:107] offset:4096
	ds_write_b64 v161, v[98:99] offset:4224
	v_mul_f32_e32 v152, 0xbfb8aa3b, v92
	v_mul_f32_e32 v153, 0xbfb8aa3b, v93
	v_mul_f32_e32 v154, 0xbfb8aa3b, v94
	v_mul_f32_e32 v155, 0xbfb8aa3b, v95
	v_mul_f32_e32 v156, 0xbfb8aa3b, v84
	v_mul_f32_e32 v157, 0xbfb8aa3b, v85
	v_mul_f32_e32 v158, 0xbfb8aa3b, v86
	v_mul_f32_e32 v159, 0xbfb8aa3b, v87
	v_exp_f32_e32 v152, v152
	v_exp_f32_e32 v153, v153
	v_exp_f32_e32 v154, v154
	v_exp_f32_e32 v155, v155
	v_exp_f32_e32 v156, v156
	v_exp_f32_e32 v157, v157
	v_exp_f32_e32 v158, v158
	v_exp_f32_e32 v159, v159
	v_add_f32_e32 v152, 1.0, v152
	v_add_f32_e32 v153, 1.0, v153
	v_add_f32_e32 v154, 1.0, v154
	v_add_f32_e32 v155, 1.0, v155
	v_add_f32_e32 v156, 1.0, v156
	v_add_f32_e32 v157, 1.0, v157
	v_add_f32_e32 v158, 1.0, v158
	v_add_f32_e32 v159, 1.0, v159
	v_rcp_f32_e32 v152, v152
	v_rcp_f32_e32 v153, v153
	v_rcp_f32_e32 v154, v154
	v_rcp_f32_e32 v155, v155
	v_rcp_f32_e32 v156, v156
	v_rcp_f32_e32 v157, v157
	v_rcp_f32_e32 v158, v158
	v_rcp_f32_e32 v159, v159
	v_mul_f32_e32 v152, v92, v152
	v_mul_f32_e32 v153, v93, v153
	v_mul_f32_e32 v154, v94, v154
	v_mul_f32_e32 v155, v95, v155
	v_mul_f32_e32 v156, v84, v156
	v_mul_f32_e32 v157, v85, v157
	v_mul_f32_e32 v158, v86, v158
	v_mul_f32_e32 v159, v87, v159
	v_mul_f32_e32 v88, v88, v152
	v_mul_f32_e32 v89, v89, v153
	v_mul_f32_e32 v90, v90, v154
	v_mul_f32_e32 v91, v91, v155
	v_mul_f32_e32 v80, v80, v156
	v_mul_f32_e32 v81, v81, v157
	v_mul_f32_e32 v82, v82, v158
	v_mul_f32_e32 v83, v83, v159
	v_cvt_pk_bf16_f32 v88, v88, v89
	v_cvt_pk_bf16_f32 v89, v90, v91
	v_cvt_pk_bf16_f32 v80, v80, v81
	v_cvt_pk_bf16_f32 v81, v82, v83
	v_mul_f32_e32 v152, 0xbfb8aa3b, v76
	v_mul_f32_e32 v153, 0xbfb8aa3b, v77
	v_mul_f32_e32 v154, 0xbfb8aa3b, v78
	v_mul_f32_e32 v155, 0xbfb8aa3b, v79
	v_mul_f32_e32 v156, 0xbfb8aa3b, v68
	v_mul_f32_e32 v157, 0xbfb8aa3b, v69
	v_mul_f32_e32 v158, 0xbfb8aa3b, v70
	v_mul_f32_e32 v159, 0xbfb8aa3b, v71
	v_exp_f32_e32 v152, v152
	v_exp_f32_e32 v153, v153
	v_exp_f32_e32 v154, v154
	v_exp_f32_e32 v155, v155
	v_exp_f32_e32 v156, v156
	v_exp_f32_e32 v157, v157
	v_exp_f32_e32 v158, v158
	v_exp_f32_e32 v159, v159
	v_add_f32_e32 v152, 1.0, v152
	v_add_f32_e32 v153, 1.0, v153
	v_add_f32_e32 v154, 1.0, v154
	v_add_f32_e32 v155, 1.0, v155
	v_add_f32_e32 v156, 1.0, v156
	v_add_f32_e32 v157, 1.0, v157
	v_add_f32_e32 v158, 1.0, v158
	v_add_f32_e32 v159, 1.0, v159
	v_rcp_f32_e32 v152, v152
	v_rcp_f32_e32 v153, v153
	v_rcp_f32_e32 v154, v154
	v_rcp_f32_e32 v155, v155
	v_rcp_f32_e32 v156, v156
	v_rcp_f32_e32 v157, v157
	v_rcp_f32_e32 v158, v158
	v_rcp_f32_e32 v159, v159
	v_mul_f32_e32 v152, v76, v152
	v_mul_f32_e32 v153, v77, v153
	v_mul_f32_e32 v154, v78, v154
	v_mul_f32_e32 v155, v79, v155
	v_mul_f32_e32 v156, v68, v156
	v_mul_f32_e32 v157, v69, v157
	v_mul_f32_e32 v158, v70, v158
	v_mul_f32_e32 v159, v71, v159
	v_mul_f32_e32 v72, v72, v152
	v_mul_f32_e32 v73, v73, v153
	v_mul_f32_e32 v74, v74, v154
	v_mul_f32_e32 v75, v75, v155
	v_mul_f32_e32 v64, v64, v156
	v_mul_f32_e32 v65, v65, v157
	v_mul_f32_e32 v66, v66, v158
	v_mul_f32_e32 v67, v67, v159
	v_cvt_pk_bf16_f32 v72, v72, v73
	v_cvt_pk_bf16_f32 v73, v74, v75
	v_cvt_pk_bf16_f32 v64, v64, v65
	v_cvt_pk_bf16_f32 v65, v66, v67
	s_waitcnt lgkmcnt(0)
	s_barrier
	ds_read_b128 v[176:179], v164
	ds_read_b128 v[180:183], v165 offset:1024
	s_waitcnt lgkmcnt(1)
	global_store_dwordx4 v[168:169], v[176:179], off sc1
	s_mov_b32 s100, 22528
	v_lshl_add_u64 v[168:169], v[168:169], 0, s[100:101]
	s_waitcnt lgkmcnt(0)
	global_store_dwordx4 v[168:169], v[180:183], off sc1
	s_mov_b32 s100, 157696
	v_lshl_add_u64 v[168:169], v[168:169], 0, s[100:101]
	s_nop 1
	ds_write_b64 v167, v[88:89] offset:0
	ds_write_b64 v167, v[80:81] offset:128
	ds_write_b64 v167, v[72:73] offset:4096
	ds_write_b64 v167, v[64:65] offset:4224
	v_mul_f32_e32 v152, 0xbfb8aa3b, v60
	v_mul_f32_e32 v153, 0xbfb8aa3b, v61
	v_mul_f32_e32 v154, 0xbfb8aa3b, v62
	v_mul_f32_e32 v155, 0xbfb8aa3b, v63
	v_mul_f32_e32 v156, 0xbfb8aa3b, v52
	v_mul_f32_e32 v157, 0xbfb8aa3b, v53
	v_mul_f32_e32 v158, 0xbfb8aa3b, v54
	v_mul_f32_e32 v159, 0xbfb8aa3b, v55
	v_exp_f32_e32 v152, v152
	v_exp_f32_e32 v153, v153
	v_exp_f32_e32 v154, v154
	v_exp_f32_e32 v155, v155
	v_exp_f32_e32 v156, v156
	v_exp_f32_e32 v157, v157
	v_exp_f32_e32 v158, v158
	v_exp_f32_e32 v159, v159
	v_add_f32_e32 v152, 1.0, v152
	v_add_f32_e32 v153, 1.0, v153
	v_add_f32_e32 v154, 1.0, v154
	v_add_f32_e32 v155, 1.0, v155
	v_add_f32_e32 v156, 1.0, v156
	v_add_f32_e32 v157, 1.0, v157
	v_add_f32_e32 v158, 1.0, v158
	v_add_f32_e32 v159, 1.0, v159
	v_rcp_f32_e32 v152, v152
	v_rcp_f32_e32 v153, v153
	v_rcp_f32_e32 v154, v154
	v_rcp_f32_e32 v155, v155
	v_rcp_f32_e32 v156, v156
	v_rcp_f32_e32 v157, v157
	v_rcp_f32_e32 v158, v158
	v_rcp_f32_e32 v159, v159
	v_mul_f32_e32 v152, v60, v152
	v_mul_f32_e32 v153, v61, v153
	v_mul_f32_e32 v154, v62, v154
	v_mul_f32_e32 v155, v63, v155
	v_mul_f32_e32 v156, v52, v156
	v_mul_f32_e32 v157, v53, v157
	v_mul_f32_e32 v158, v54, v158
	v_mul_f32_e32 v159, v55, v159
	v_mul_f32_e32 v56, v56, v152
	v_mul_f32_e32 v57, v57, v153
	v_mul_f32_e32 v58, v58, v154
	v_mul_f32_e32 v59, v59, v155
	v_mul_f32_e32 v48, v48, v156
	v_mul_f32_e32 v49, v49, v157
	v_mul_f32_e32 v50, v50, v158
	v_mul_f32_e32 v51, v51, v159
	v_cvt_pk_bf16_f32 v56, v56, v57
	v_cvt_pk_bf16_f32 v57, v58, v59
	v_cvt_pk_bf16_f32 v48, v48, v49
	v_cvt_pk_bf16_f32 v49, v50, v51
	v_mul_f32_e32 v152, 0xbfb8aa3b, v44
	v_mul_f32_e32 v153, 0xbfb8aa3b, v45
	v_mul_f32_e32 v154, 0xbfb8aa3b, v46
	v_mul_f32_e32 v155, 0xbfb8aa3b, v47
	v_mul_f32_e32 v156, 0xbfb8aa3b, v36
	v_mul_f32_e32 v157, 0xbfb8aa3b, v37
	v_mul_f32_e32 v158, 0xbfb8aa3b, v38
	v_mul_f32_e32 v159, 0xbfb8aa3b, v39
	v_exp_f32_e32 v152, v152
	v_exp_f32_e32 v153, v153
	v_exp_f32_e32 v154, v154
	v_exp_f32_e32 v155, v155
	v_exp_f32_e32 v156, v156
	v_exp_f32_e32 v157, v157
	v_exp_f32_e32 v158, v158
	v_exp_f32_e32 v159, v159
	v_add_f32_e32 v152, 1.0, v152
	v_add_f32_e32 v153, 1.0, v153
	v_add_f32_e32 v154, 1.0, v154
	v_add_f32_e32 v155, 1.0, v155
	v_add_f32_e32 v156, 1.0, v156
	v_add_f32_e32 v157, 1.0, v157
	v_add_f32_e32 v158, 1.0, v158
	v_add_f32_e32 v159, 1.0, v159
	v_rcp_f32_e32 v152, v152
	v_rcp_f32_e32 v153, v153
	v_rcp_f32_e32 v154, v154
	v_rcp_f32_e32 v155, v155
	v_rcp_f32_e32 v156, v156
	v_rcp_f32_e32 v157, v157
	v_rcp_f32_e32 v158, v158
	v_rcp_f32_e32 v159, v159
	v_mul_f32_e32 v152, v44, v152
	v_mul_f32_e32 v153, v45, v153
	v_mul_f32_e32 v154, v46, v154
	v_mul_f32_e32 v155, v47, v155
	v_mul_f32_e32 v156, v36, v156
	v_mul_f32_e32 v157, v37, v157
	v_mul_f32_e32 v158, v38, v158
	v_mul_f32_e32 v159, v39, v159
	v_mul_f32_e32 v40, v40, v152
	v_mul_f32_e32 v41, v41, v153
	v_mul_f32_e32 v42, v42, v154
	v_mul_f32_e32 v43, v43, v155
	v_mul_f32_e32 v32, v32, v156
	v_mul_f32_e32 v33, v33, v157
	v_mul_f32_e32 v34, v34, v158
	v_mul_f32_e32 v35, v35, v159
	v_cvt_pk_bf16_f32 v40, v40, v41
	v_cvt_pk_bf16_f32 v41, v42, v43
	v_cvt_pk_bf16_f32 v32, v32, v33
	v_cvt_pk_bf16_f32 v33, v34, v35
	s_waitcnt lgkmcnt(0)
	s_barrier
	ds_read_b128 v[176:179], v174
	ds_read_b128 v[180:183], v175 offset:1024
	s_waitcnt lgkmcnt(1)
	global_store_dwordx4 v[168:169], v[176:179], off sc1
	s_mov_b32 s100, 22528
	v_lshl_add_u64 v[168:169], v[168:169], 0, s[100:101]
	s_waitcnt lgkmcnt(0)
	global_store_dwordx4 v[168:169], v[180:183], off sc1
	s_mov_b32 s100, 518144
	v_lshl_add_u64 v[168:169], v[168:169], 0, s[100:101]
	s_nop 1
	ds_write_b64 v161, v[56:57] offset:0
	ds_write_b64 v161, v[48:49] offset:128
	ds_write_b64 v161, v[40:41] offset:4096
	ds_write_b64 v161, v[32:33] offset:4224
	v_mul_f32_e32 v152, 0xbfb8aa3b, v28
	v_mul_f32_e32 v153, 0xbfb8aa3b, v29
	v_mul_f32_e32 v154, 0xbfb8aa3b, v30
	v_mul_f32_e32 v155, 0xbfb8aa3b, v31
	v_mul_f32_e32 v156, 0xbfb8aa3b, v20
	v_mul_f32_e32 v157, 0xbfb8aa3b, v21
	v_mul_f32_e32 v158, 0xbfb8aa3b, v22
	v_mul_f32_e32 v159, 0xbfb8aa3b, v23
	v_exp_f32_e32 v152, v152
	v_exp_f32_e32 v153, v153
	v_exp_f32_e32 v154, v154
	v_exp_f32_e32 v155, v155
	v_exp_f32_e32 v156, v156
	v_exp_f32_e32 v157, v157
	v_exp_f32_e32 v158, v158
	v_exp_f32_e32 v159, v159
	v_add_f32_e32 v152, 1.0, v152
	v_add_f32_e32 v153, 1.0, v153
	v_add_f32_e32 v154, 1.0, v154
	v_add_f32_e32 v155, 1.0, v155
	v_add_f32_e32 v156, 1.0, v156
	v_add_f32_e32 v157, 1.0, v157
	v_add_f32_e32 v158, 1.0, v158
	v_add_f32_e32 v159, 1.0, v159
	v_rcp_f32_e32 v152, v152
	v_rcp_f32_e32 v153, v153
	v_rcp_f32_e32 v154, v154
	v_rcp_f32_e32 v155, v155
	v_rcp_f32_e32 v156, v156
	v_rcp_f32_e32 v157, v157
	v_rcp_f32_e32 v158, v158
	v_rcp_f32_e32 v159, v159
	v_mul_f32_e32 v152, v28, v152
	v_mul_f32_e32 v153, v29, v153
	v_mul_f32_e32 v154, v30, v154
	v_mul_f32_e32 v155, v31, v155
	v_mul_f32_e32 v156, v20, v156
	v_mul_f32_e32 v157, v21, v157
	v_mul_f32_e32 v158, v22, v158
	v_mul_f32_e32 v159, v23, v159
	v_mul_f32_e32 v24, v24, v152
	v_mul_f32_e32 v25, v25, v153
	v_mul_f32_e32 v26, v26, v154
	v_mul_f32_e32 v27, v27, v155
	v_mul_f32_e32 v16, v16, v156
	v_mul_f32_e32 v17, v17, v157
	v_mul_f32_e32 v18, v18, v158
	v_mul_f32_e32 v19, v19, v159
	v_cvt_pk_bf16_f32 v24, v24, v25
	v_cvt_pk_bf16_f32 v25, v26, v27
	v_cvt_pk_bf16_f32 v16, v16, v17
	v_cvt_pk_bf16_f32 v17, v18, v19
	s_mov_b64 s[24:25], -1
	v_mul_f32_e32 v152, 0xbfb8aa3b, v12
	v_mul_f32_e32 v153, 0xbfb8aa3b, v13
	v_mul_f32_e32 v154, 0xbfb8aa3b, v14
	v_mul_f32_e32 v155, 0xbfb8aa3b, v15
	v_mul_f32_e32 v156, 0xbfb8aa3b, v4
	v_mul_f32_e32 v157, 0xbfb8aa3b, v5
	v_mul_f32_e32 v158, 0xbfb8aa3b, v6
	v_mul_f32_e32 v159, 0xbfb8aa3b, v7
	v_exp_f32_e32 v152, v152
	v_exp_f32_e32 v153, v153
	v_exp_f32_e32 v154, v154
	v_exp_f32_e32 v155, v155
	v_exp_f32_e32 v156, v156
	v_exp_f32_e32 v157, v157
	v_exp_f32_e32 v158, v158
	v_exp_f32_e32 v159, v159
	v_add_f32_e32 v152, 1.0, v152
	v_add_f32_e32 v153, 1.0, v153
	v_add_f32_e32 v154, 1.0, v154
	v_add_f32_e32 v155, 1.0, v155
	v_add_f32_e32 v156, 1.0, v156
	v_add_f32_e32 v157, 1.0, v157
	v_add_f32_e32 v158, 1.0, v158
	v_add_f32_e32 v159, 1.0, v159
	v_rcp_f32_e32 v152, v152
	v_rcp_f32_e32 v153, v153
	v_rcp_f32_e32 v154, v154
	v_rcp_f32_e32 v155, v155
	v_rcp_f32_e32 v156, v156
	v_rcp_f32_e32 v157, v157
	v_rcp_f32_e32 v158, v158
	v_rcp_f32_e32 v159, v159
	v_mul_f32_e32 v152, v12, v152
	v_mul_f32_e32 v153, v13, v153
	v_mul_f32_e32 v154, v14, v154
	v_mul_f32_e32 v155, v15, v155
	v_mul_f32_e32 v156, v4, v156
	v_mul_f32_e32 v157, v5, v157
	v_mul_f32_e32 v158, v6, v158
	v_mul_f32_e32 v159, v7, v159
	v_mul_f32_e32 v8, v8, v152
	v_mul_f32_e32 v9, v9, v153
	v_mul_f32_e32 v10, v10, v154
	v_mul_f32_e32 v11, v11, v155
	v_mul_f32_e32 v0, v0, v156
	v_mul_f32_e32 v1, v1, v157
	v_mul_f32_e32 v2, v2, v158
	v_mul_f32_e32 v3, v3, v159
	v_cvt_pk_bf16_f32 v8, v8, v9
	v_cvt_pk_bf16_f32 v9, v10, v11
	v_cvt_pk_bf16_f32 v0, v0, v1
	v_cvt_pk_bf16_f32 v1, v2, v3
	s_waitcnt lgkmcnt(0)
	s_barrier
	ds_read_b128 v[176:179], v164
	ds_read_b128 v[180:183], v165 offset:1024
	s_waitcnt lgkmcnt(1)
	global_store_dwordx4 v[168:169], v[176:179], off sc1
	s_mov_b32 s100, 22528
	v_lshl_add_u64 v[168:169], v[168:169], 0, s[100:101]
	s_waitcnt lgkmcnt(0)
	global_store_dwordx4 v[168:169], v[180:183], off sc1
	s_mov_b32 s100, 157696
	v_lshl_add_u64 v[168:169], v[168:169], 0, s[100:101]
	s_nop 1
	ds_write_b64 v167, v[24:25] offset:0
	ds_write_b64 v167, v[16:17] offset:128
	ds_write_b64 v167, v[8:9] offset:4096
	ds_write_b64 v167, v[0:1] offset:4224
	s_waitcnt lgkmcnt(0)
	s_barrier
	ds_read_b128 v[176:179], v174
	ds_read_b128 v[180:183], v175 offset:1024
	s_waitcnt lgkmcnt(1)
	global_store_dwordx4 v[168:169], v[176:179], off sc1
	s_mov_b32 s100, 22528
	v_lshl_add_u64 v[168:169], v[168:169], 0, s[100:101]
	s_waitcnt lgkmcnt(0)
	global_store_dwordx4 v[168:169], v[180:183], off sc1
	s_nop 1
	s_cbranch_vccnz .LBB0_729
	s_andn2_b64 vcc, exec, s[4:5]
	s_cbranch_vccnz .LBB0_728
	s_barrier
	s_branch .LBB0_728

.LBB0_752:
	v_ashrrev_i32_e32 v19, 31, v5
	v_mul_lo_u32 v22, s67, v5
	v_mul_lo_u32 v19, s66, v19
	v_mad_u64_u32 v[20:21], s[30:31], s66, v5, 0
	v_add3_u32 v21, v21, v19, v22
	v_lshl_add_u64 v[6:7], v[20:21], 1, v[6:7]
	global_store_dwordx4 v[6:7], v[0:3], off sc1
	s_waitcnt lgkmcnt(0)
	s_add_i32 s34, s34, s95
	s_cmp_lt_i32 s34, s35
	s_cbranch_scc0 .LBB0_793

.LBB0_771:
	s_lshl_b64 s[30:31], s[72:73], 1
	s_add_u32 s30, s70, s30
	s_addc_u32 s31, s71, s31
	v_mov_b32_e32 v5, v97
	v_lshl_add_u64 v[6:7], s[30:31], 0, v[4:5]
	v_ashrrev_i32_e32 v5, 31, v20
	v_mul_lo_u32 v22, s67, v20
	v_mul_lo_u32 v5, s66, v5
	v_mad_u64_u32 v[20:21], s[30:31], s66, v20, 0
	v_add3_u32 v21, v21, v5, v22
	v_lshl_add_u64 v[20:21], v[20:21], 1, v[6:7]
	global_store_dwordx4 v[20:21], v[0:3], off sc1
	ds_read2_b32 v[0:1], v10 offset0:8 offset1:41
	s_cmp_gt_i32 s77, 1
	s_waitcnt lgkmcnt(0)
	v_cvt_pk_bf16_f32 v0, v0, v1
	ds_read2_b32 v[2:3], v10 offset0:74 offset1:107
	s_waitcnt lgkmcnt(0)
	v_cvt_pk_bf16_f32 v1, v2, v3
	ds_read2_b32 v[2:3], v10 offset0:140 offset1:173
	s_mov_b64 s[70:71], -1
	s_waitcnt lgkmcnt(0)
	v_cvt_pk_bf16_f32 v2, v2, v3
	ds_read2_b32 v[20:21], v10 offset0:206 offset1:239
	s_waitcnt lgkmcnt(0)
	v_cvt_pk_bf16_f32 v3, v20, v21
	s_cbranch_scc0 .LBB0_773
	v_or_b32_e32 v5, v19, v13
	s_mov_b64 s[70:71], 0

.LBB0_778:
	v_ashrrev_i32_e32 v20, 31, v5
	v_mul_lo_u32 v22, s67, v5
	v_mul_lo_u32 v23, s66, v20
	v_mad_u64_u32 v[20:21], s[30:31], s66, v5, 0
	v_add3_u32 v21, v21, v23, v22
	v_lshl_add_u64 v[20:21], v[20:21], 1, v[6:7]
	global_store_dwordx4 v[20:21], v[0:3], off sc1
	ds_read2_b32 v[0:1], v10 offset0:16 offset1:49
	s_cmp_gt_i32 s77, 1
	s_waitcnt lgkmcnt(0)
	v_cvt_pk_bf16_f32 v0, v0, v1
	ds_read2_b32 v[2:3], v10 offset0:82 offset1:115
	s_waitcnt lgkmcnt(0)
	v_cvt_pk_bf16_f32 v1, v2, v3
	ds_read2_b32 v[2:3], v10 offset0:148 offset1:181
	s_mov_b64 s[70:71], -1
	s_waitcnt lgkmcnt(0)
	v_cvt_pk_bf16_f32 v2, v2, v3
	ds_read2_b32 v[20:21], v10 offset0:214 offset1:247
	s_waitcnt lgkmcnt(0)
	v_cvt_pk_bf16_f32 v3, v20, v21
	s_cbranch_scc0 .LBB0_780
	v_or_b32_e32 v5, v19, v15
	s_mov_b64 s[70:71], 0

.LBB0_785:
	v_ashrrev_i32_e32 v20, 31, v5
	v_mul_lo_u32 v22, s67, v5
	v_mul_lo_u32 v23, s66, v20
	v_mad_u64_u32 v[20:21], s[30:31], s66, v5, 0
	v_add3_u32 v21, v21, v23, v22
	v_lshl_add_u64 v[20:21], v[20:21], 1, v[6:7]
	global_store_dwordx4 v[20:21], v[0:3], off sc1
	ds_read2_b32 v[0:1], v10 offset0:24 offset1:57
	s_cmp_gt_i32 s77, 1
	s_waitcnt lgkmcnt(0)
	v_cvt_pk_bf16_f32 v0, v0, v1
	ds_read2_b32 v[2:3], v10 offset0:90 offset1:123
	s_waitcnt lgkmcnt(0)
	v_cvt_pk_bf16_f32 v1, v2, v3
	ds_read2_b32 v[2:3], v10 offset0:156 offset1:189
	s_mov_b64 s[70:71], -1
	s_waitcnt lgkmcnt(0)
	v_cvt_pk_bf16_f32 v2, v2, v3
	ds_read2_b32 v[20:21], v10 offset0:222 offset1:255
	s_waitcnt lgkmcnt(0)
	v_cvt_pk_bf16_f32 v3, v20, v21
	s_cbranch_scc0 .LBB0_787
	v_or_b32_e32 v5, v19, v17
	s_mov_b64 s[70:71], 0

.LBB0_1001:
	s_or_b64 exec, exec, s[4:5]
	v_readlane_b32 s4, v255, 1
	v_readlane_b32 s6, v255, 14
	s_waitcnt lgkmcnt(0)
	s_barrier
	v_readlane_b32 s5, v255, 2
	v_readlane_b32 s7, v255, 15
	s_and_b64 s[4:5], s[4:5], s[6:7]
	s_andn2_b64 vcc, exec, s[4:5]
	s_mov_b64 s[4:5], -1
	s_cbranch_vccz .LBB0_1003
	v_lshl_add_u32 v162, v253, 3, s65
	v_ashrrev_i32_e32 v163, 31, v162
	v_lshl_add_u32 v178, v252, 2, s13
	v_lshl_add_u64 v[162:163], v[162:163], 1, s[18:19]
	s_mov_b64 s[4:5], 0x5000000
	ds_read_b32 v170, v178 offset:4096
	v_lshl_add_u64 v[162:163], v[162:163], 0, s[4:5]
	s_add_i32 s4, s26, s64
	v_add_u32_e32 v164, s4, v252
	v_ashrrev_i32_e32 v165, 31, v164
	v_lshlrev_b64 v[166:167], 11, v[164:165]
	v_lshl_add_u64 v[172:173], v[162:163], 0, v[166:167]
	s_waitcnt lgkmcnt(0)
	v_pk_mul_f32 v[166:167], v[126:127], v[170:171] op_sel_hi:[1,0]
	v_pk_mul_f32 v[168:169], v[128:129], v[170:171] op_sel_hi:[1,0]
	s_waitcnt vmcnt(19)
	v_pk_fma_f32 v[166:167], v[138:139], v[166:167], v[154:155]
	v_pk_fma_f32 v[168:169], v[140:141], v[168:169], v[156:157]
	v_pk_mul_f32 v[174:175], v[122:123], v[170:171] op_sel_hi:[1,0]
	v_pk_mul_f32 v[176:177], v[124:125], v[170:171] op_sel_hi:[1,0]
	s_waitcnt vmcnt(17)
	v_pk_fma_f32 v[174:175], v[130:131], v[174:175], v[158:159]
	v_pk_fma_f32 v[176:177], v[132:133], v[176:177], v[160:161]
	v_cvt_pk_bf16_f32 v166, v166, v167
	v_cvt_pk_bf16_f32 v167, v168, v169
	v_cvt_pk_bf16_f32 v168, v174, v175
	v_pk_mul_f32 v[174:175], v[106:107], v[170:171] op_sel_hi:[1,0]
	v_cvt_pk_bf16_f32 v169, v176, v177
	global_store_dwordx4 v[172:173], v[166:169], off sc1
	v_pk_fma_f32 v[174:175], v[134:135], v[174:175], v[146:147]
	s_mov_b64 s[4:5], 0
	v_pk_mul_f32 v[166:167], v[114:115], v[170:171] op_sel_hi:[1,0]
	v_pk_mul_f32 v[168:169], v[116:117], v[170:171] op_sel_hi:[1,0]
	s_waitcnt vmcnt(17)
	v_pk_fma_f32 v[166:167], v[142:143], v[166:167], v[150:151]
	v_pk_fma_f32 v[168:169], v[144:145], v[168:169], v[152:153]
	v_pk_mul_f32 v[170:171], v[108:109], v[170:171] op_sel_hi:[1,0]
	v_cvt_pk_bf16_f32 v166, v166, v167
	v_cvt_pk_bf16_f32 v167, v168, v169
	v_cvt_pk_bf16_f32 v168, v174, v175
	s_nop 0
	v_pk_fma_f32 v[170:171], v[136:137], v[170:171], v[148:149]
	s_nop 0
	v_cvt_pk_bf16_f32 v169, v170, v171
	global_store_dwordx4 v[172:173], v[166:169], off offset:256 sc1
	ds_read_b32 v170, v178 offset:4160
	s_waitcnt lgkmcnt(0)
	v_pk_mul_f32 v[174:175], v[110:111], v[170:171] op_sel_hi:[1,0]
	v_add_u32_e32 v166, 16, v164
	v_ashrrev_i32_e32 v167, 31, v166
	v_lshlrev_b64 v[166:167], 11, v[166:167]
	v_lshl_add_u64 v[172:173], v[162:163], 0, v[166:167]
	v_pk_mul_f32 v[166:167], v[118:119], v[170:171] op_sel_hi:[1,0]
	v_pk_mul_f32 v[168:169], v[120:121], v[170:171] op_sel_hi:[1,0]
	v_pk_fma_f32 v[166:167], v[138:139], v[166:167], v[154:155]
	v_pk_fma_f32 v[168:169], v[140:141], v[168:169], v[156:157]
	v_pk_mul_f32 v[176:177], v[112:113], v[170:171] op_sel_hi:[1,0]
	v_pk_fma_f32 v[174:175], v[130:131], v[174:175], v[158:159]
	v_pk_fma_f32 v[176:177], v[132:133], v[176:177], v[160:161]
	v_cvt_pk_bf16_f32 v166, v166, v167
	v_cvt_pk_bf16_f32 v167, v168, v169
	v_cvt_pk_bf16_f32 v168, v174, v175
	v_pk_mul_f32 v[174:175], v[88:89], v[170:171] op_sel_hi:[1,0]
	v_cvt_pk_bf16_f32 v169, v176, v177
	global_store_dwordx4 v[172:173], v[166:169], off sc1
	v_pk_fma_f32 v[174:175], v[134:135], v[174:175], v[146:147]
	s_nop 0
	v_pk_mul_f32 v[166:167], v[98:99], v[170:171] op_sel_hi:[1,0]
	v_pk_mul_f32 v[168:169], v[100:101], v[170:171] op_sel_hi:[1,0]
	v_pk_fma_f32 v[166:167], v[142:143], v[166:167], v[150:151]
	v_pk_fma_f32 v[168:169], v[144:145], v[168:169], v[152:153]
	v_pk_mul_f32 v[170:171], v[90:91], v[170:171] op_sel_hi:[1,0]
	v_cvt_pk_bf16_f32 v166, v166, v167
	v_cvt_pk_bf16_f32 v167, v168, v169
	v_cvt_pk_bf16_f32 v168, v174, v175
	s_nop 0
	v_pk_fma_f32 v[170:171], v[136:137], v[170:171], v[148:149]
	s_nop 0
	v_cvt_pk_bf16_f32 v169, v170, v171
	global_store_dwordx4 v[172:173], v[166:169], off offset:256 sc1
	ds_read_b32 v170, v178 offset:4224
	s_waitcnt lgkmcnt(0)
	v_pk_mul_f32 v[174:175], v[92:93], v[170:171] op_sel_hi:[1,0]
	v_add_u32_e32 v166, 32, v164
	v_ashrrev_i32_e32 v167, 31, v166
	v_lshlrev_b64 v[166:167], 11, v[166:167]
	v_lshl_add_u64 v[172:173], v[162:163], 0, v[166:167]
	v_pk_mul_f32 v[166:167], v[102:103], v[170:171] op_sel_hi:[1,0]
	v_pk_mul_f32 v[168:169], v[104:105], v[170:171] op_sel_hi:[1,0]
	v_pk_fma_f32 v[166:167], v[138:139], v[166:167], v[154:155]
	v_pk_fma_f32 v[168:169], v[140:141], v[168:169], v[156:157]
	v_pk_mul_f32 v[176:177], v[94:95], v[170:171] op_sel_hi:[1,0]
	v_pk_fma_f32 v[174:175], v[130:131], v[174:175], v[158:159]
	v_pk_fma_f32 v[176:177], v[132:133], v[176:177], v[160:161]
	v_cvt_pk_bf16_f32 v166, v166, v167
	v_cvt_pk_bf16_f32 v167, v168, v169
	v_cvt_pk_bf16_f32 v168, v174, v175
	v_pk_mul_f32 v[174:175], v[72:73], v[170:171] op_sel_hi:[1,0]
	v_cvt_pk_bf16_f32 v169, v176, v177
	global_store_dwordx4 v[172:173], v[166:169], off sc1
	v_pk_fma_f32 v[174:175], v[134:135], v[174:175], v[146:147]
	s_nop 0
	v_pk_mul_f32 v[166:167], v[80:81], v[170:171] op_sel_hi:[1,0]
	v_pk_mul_f32 v[168:169], v[82:83], v[170:171] op_sel_hi:[1,0]
	v_pk_fma_f32 v[166:167], v[142:143], v[166:167], v[150:151]
	v_pk_fma_f32 v[168:169], v[144:145], v[168:169], v[152:153]
	v_pk_mul_f32 v[170:171], v[74:75], v[170:171] op_sel_hi:[1,0]
	v_cvt_pk_bf16_f32 v166, v166, v167
	v_cvt_pk_bf16_f32 v167, v168, v169
	v_cvt_pk_bf16_f32 v168, v174, v175
	s_nop 0
	v_pk_fma_f32 v[170:171], v[136:137], v[170:171], v[148:149]
	s_nop 0
	v_cvt_pk_bf16_f32 v169, v170, v171
	global_store_dwordx4 v[172:173], v[166:169], off offset:256 sc1
	ds_read_b32 v170, v178 offset:4288
	s_waitcnt lgkmcnt(0)
	v_pk_mul_f32 v[174:175], v[76:77], v[170:171] op_sel_hi:[1,0]
	v_add_u32_e32 v166, 48, v164
	v_ashrrev_i32_e32 v167, 31, v166
	v_lshlrev_b64 v[166:167], 11, v[166:167]
	v_lshl_add_u64 v[172:173], v[162:163], 0, v[166:167]
	v_pk_mul_f32 v[166:167], v[84:85], v[170:171] op_sel_hi:[1,0]
	v_pk_mul_f32 v[168:169], v[86:87], v[170:171] op_sel_hi:[1,0]
	v_pk_fma_f32 v[166:167], v[138:139], v[166:167], v[154:155]
	v_pk_fma_f32 v[168:169], v[140:141], v[168:169], v[156:157]
	v_pk_mul_f32 v[176:177], v[78:79], v[170:171] op_sel_hi:[1,0]
	v_pk_fma_f32 v[174:175], v[130:131], v[174:175], v[158:159]
	v_pk_fma_f32 v[176:177], v[132:133], v[176:177], v[160:161]
	v_cvt_pk_bf16_f32 v166, v166, v167
	v_cvt_pk_bf16_f32 v167, v168, v169
	v_cvt_pk_bf16_f32 v168, v174, v175
	v_pk_mul_f32 v[174:175], v[64:65], v[170:171] op_sel_hi:[1,0]
	v_cvt_pk_bf16_f32 v169, v176, v177
	global_store_dwordx4 v[172:173], v[166:169], off sc1
	v_pk_fma_f32 v[174:175], v[134:135], v[174:175], v[146:147]
	s_nop 0
	v_pk_mul_f32 v[166:167], v[68:69], v[170:171] op_sel_hi:[1,0]
	v_pk_mul_f32 v[168:169], v[70:71], v[170:171] op_sel_hi:[1,0]
	v_pk_fma_f32 v[166:167], v[142:143], v[166:167], v[150:151]
	v_pk_fma_f32 v[168:169], v[144:145], v[168:169], v[152:153]
	v_pk_mul_f32 v[170:171], v[66:67], v[170:171] op_sel_hi:[1,0]
	v_cvt_pk_bf16_f32 v166, v166, v167
	v_cvt_pk_bf16_f32 v167, v168, v169
	v_cvt_pk_bf16_f32 v168, v174, v175
	s_nop 0
	v_pk_fma_f32 v[170:171], v[136:137], v[170:171], v[148:149]
	s_nop 0
	v_cvt_pk_bf16_f32 v169, v170, v171
	global_store_dwordx4 v[172:173], v[166:169], off offset:256 sc1
	ds_read_b32 v170, v178 offset:4608
	s_waitcnt lgkmcnt(0)
	v_pk_mul_f32 v[174:175], v[56:57], v[170:171] op_sel_hi:[1,0]
	v_add_u32_e32 v166, 0x80, v164
	v_ashrrev_i32_e32 v167, 31, v166
	v_lshlrev_b64 v[166:167], 11, v[166:167]
	v_lshl_add_u64 v[172:173], v[162:163], 0, v[166:167]
	v_pk_mul_f32 v[166:167], v[60:61], v[170:171] op_sel_hi:[1,0]
	v_pk_mul_f32 v[168:169], v[62:63], v[170:171] op_sel_hi:[1,0]
	v_pk_fma_f32 v[166:167], v[138:139], v[166:167], v[154:155]
	v_pk_fma_f32 v[168:169], v[140:141], v[168:169], v[156:157]
	v_pk_mul_f32 v[176:177], v[58:59], v[170:171] op_sel_hi:[1,0]
	v_pk_fma_f32 v[174:175], v[130:131], v[174:175], v[158:159]
	v_pk_fma_f32 v[176:177], v[132:133], v[176:177], v[160:161]
	v_cvt_pk_bf16_f32 v166, v166, v167
	v_cvt_pk_bf16_f32 v167, v168, v169
	v_cvt_pk_bf16_f32 v168, v174, v175
	v_pk_mul_f32 v[174:175], v[40:41], v[170:171] op_sel_hi:[1,0]
	v_cvt_pk_bf16_f32 v169, v176, v177
	global_store_dwordx4 v[172:173], v[166:169], off sc1
	v_pk_fma_f32 v[174:175], v[134:135], v[174:175], v[146:147]
	s_nop 0
	v_pk_mul_f32 v[166:167], v[48:49], v[170:171] op_sel_hi:[1,0]
	v_pk_mul_f32 v[168:169], v[50:51], v[170:171] op_sel_hi:[1,0]
	v_pk_fma_f32 v[166:167], v[142:143], v[166:167], v[150:151]
	v_pk_fma_f32 v[168:169], v[144:145], v[168:169], v[152:153]
	v_pk_mul_f32 v[170:171], v[42:43], v[170:171] op_sel_hi:[1,0]
	v_cvt_pk_bf16_f32 v166, v166, v167
	v_cvt_pk_bf16_f32 v167, v168, v169
	v_cvt_pk_bf16_f32 v168, v174, v175
	s_nop 0
	v_pk_fma_f32 v[170:171], v[136:137], v[170:171], v[148:149]
	s_nop 0
	v_cvt_pk_bf16_f32 v169, v170, v171
	global_store_dwordx4 v[172:173], v[166:169], off offset:256 sc1
	ds_read_b32 v170, v178 offset:4672
	s_waitcnt lgkmcnt(0)
	v_pk_mul_f32 v[174:175], v[44:45], v[170:171] op_sel_hi:[1,0]
	v_add_u32_e32 v166, 0x90, v164
	v_ashrrev_i32_e32 v167, 31, v166
	v_lshlrev_b64 v[166:167], 11, v[166:167]
	v_lshl_add_u64 v[172:173], v[162:163], 0, v[166:167]
	v_pk_mul_f32 v[166:167], v[52:53], v[170:171] op_sel_hi:[1,0]
	v_pk_mul_f32 v[168:169], v[54:55], v[170:171] op_sel_hi:[1,0]
	v_pk_fma_f32 v[166:167], v[138:139], v[166:167], v[154:155]
	v_pk_fma_f32 v[168:169], v[140:141], v[168:169], v[156:157]
	v_pk_mul_f32 v[176:177], v[46:47], v[170:171] op_sel_hi:[1,0]
	v_pk_fma_f32 v[174:175], v[130:131], v[174:175], v[158:159]
	v_pk_fma_f32 v[176:177], v[132:133], v[176:177], v[160:161]
	v_cvt_pk_bf16_f32 v166, v166, v167
	v_cvt_pk_bf16_f32 v167, v168, v169
	v_cvt_pk_bf16_f32 v168, v174, v175
	v_pk_mul_f32 v[174:175], v[24:25], v[170:171] op_sel_hi:[1,0]
	v_cvt_pk_bf16_f32 v169, v176, v177
	global_store_dwordx4 v[172:173], v[166:169], off sc1
	v_pk_fma_f32 v[174:175], v[134:135], v[174:175], v[146:147]
	s_nop 0
	v_pk_mul_f32 v[166:167], v[32:33], v[170:171] op_sel_hi:[1,0]
	v_pk_mul_f32 v[168:169], v[34:35], v[170:171] op_sel_hi:[1,0]
	v_pk_fma_f32 v[166:167], v[142:143], v[166:167], v[150:151]
	v_pk_fma_f32 v[168:169], v[144:145], v[168:169], v[152:153]
	v_pk_mul_f32 v[170:171], v[26:27], v[170:171] op_sel_hi:[1,0]
	v_cvt_pk_bf16_f32 v166, v166, v167
	v_cvt_pk_bf16_f32 v167, v168, v169
	v_cvt_pk_bf16_f32 v168, v174, v175
	s_nop 0
	v_pk_fma_f32 v[170:171], v[136:137], v[170:171], v[148:149]
	s_nop 0
	v_cvt_pk_bf16_f32 v169, v170, v171
	global_store_dwordx4 v[172:173], v[166:169], off offset:256 sc1
	ds_read_b32 v170, v178 offset:4736
	s_waitcnt lgkmcnt(0)
	v_pk_mul_f32 v[174:175], v[28:29], v[170:171] op_sel_hi:[1,0]
	v_add_u32_e32 v166, 0xa0, v164
	v_ashrrev_i32_e32 v167, 31, v166
	v_lshlrev_b64 v[166:167], 11, v[166:167]
	v_lshl_add_u64 v[172:173], v[162:163], 0, v[166:167]
	v_pk_mul_f32 v[166:167], v[36:37], v[170:171] op_sel_hi:[1,0]
	v_pk_mul_f32 v[168:169], v[38:39], v[170:171] op_sel_hi:[1,0]
	v_pk_fma_f32 v[166:167], v[138:139], v[166:167], v[154:155]
	v_pk_fma_f32 v[168:169], v[140:141], v[168:169], v[156:157]
	v_pk_mul_f32 v[176:177], v[30:31], v[170:171] op_sel_hi:[1,0]
	v_pk_fma_f32 v[174:175], v[130:131], v[174:175], v[158:159]
	v_pk_fma_f32 v[176:177], v[132:133], v[176:177], v[160:161]
	v_cvt_pk_bf16_f32 v166, v166, v167
	v_cvt_pk_bf16_f32 v167, v168, v169
	v_cvt_pk_bf16_f32 v168, v174, v175
	v_pk_mul_f32 v[174:175], v[8:9], v[170:171] op_sel_hi:[1,0]
	v_cvt_pk_bf16_f32 v169, v176, v177
	global_store_dwordx4 v[172:173], v[166:169], off sc1
	v_pk_fma_f32 v[174:175], v[134:135], v[174:175], v[146:147]
	v_add_u32_e32 v164, 0xb0, v164
	v_pk_mul_f32 v[166:167], v[16:17], v[170:171] op_sel_hi:[1,0]
	v_pk_mul_f32 v[168:169], v[18:19], v[170:171] op_sel_hi:[1,0]
	v_pk_fma_f32 v[166:167], v[142:143], v[166:167], v[150:151]
	v_pk_fma_f32 v[168:169], v[144:145], v[168:169], v[152:153]
	v_pk_mul_f32 v[170:171], v[10:11], v[170:171] op_sel_hi:[1,0]
	v_cvt_pk_bf16_f32 v166, v166, v167
	v_cvt_pk_bf16_f32 v167, v168, v169
	v_cvt_pk_bf16_f32 v168, v174, v175
	v_ashrrev_i32_e32 v165, 31, v164
	v_pk_fma_f32 v[170:171], v[136:137], v[170:171], v[148:149]
	v_lshlrev_b64 v[164:165], 11, v[164:165]
	v_cvt_pk_bf16_f32 v169, v170, v171
	global_store_dwordx4 v[172:173], v[166:169], off offset:256 sc1
	ds_read_b32 v166, v178 offset:4800
	v_lshl_add_u64 v[162:163], v[162:163], 0, v[164:165]
	s_waitcnt lgkmcnt(0)
	v_pk_mul_f32 v[164:165], v[20:21], v[166:167] op_sel_hi:[1,0]
	v_pk_mul_f32 v[168:169], v[22:23], v[166:167] op_sel_hi:[1,0]
	v_pk_fma_f32 v[138:139], v[138:139], v[164:165], v[154:155]
	v_pk_fma_f32 v[140:141], v[140:141], v[168:169], v[156:157]
	v_pk_mul_f32 v[154:155], v[12:13], v[166:167] op_sel_hi:[1,0]
	v_pk_mul_f32 v[156:157], v[14:15], v[166:167] op_sel_hi:[1,0]
	s_nop 0
	v_pk_fma_f32 v[156:157], v[132:133], v[156:157], v[160:161]
	v_pk_fma_f32 v[132:133], v[130:131], v[154:155], v[158:159]
	v_cvt_pk_bf16_f32 v130, v138, v139
	v_cvt_pk_bf16_f32 v131, v140, v141
	v_pk_mul_f32 v[138:139], v[0:1], v[166:167] op_sel_hi:[1,0]
	v_cvt_pk_bf16_f32 v132, v132, v133
	v_cvt_pk_bf16_f32 v133, v156, v157
	global_store_dwordx4 v[162:163], v[130:133], off sc1
	v_pk_mul_f32 v[140:141], v[2:3], v[166:167] op_sel_hi:[1,0]
	v_pk_fma_f32 v[134:135], v[134:135], v[138:139], v[146:147]
	v_pk_mul_f32 v[130:131], v[4:5], v[166:167] op_sel_hi:[1,0]
	v_pk_mul_f32 v[132:133], v[6:7], v[166:167] op_sel_hi:[1,0]
	v_pk_fma_f32 v[130:131], v[142:143], v[130:131], v[150:151]
	v_pk_fma_f32 v[132:133], v[144:145], v[132:133], v[152:153]
	v_pk_fma_f32 v[136:137], v[136:137], v[140:141], v[148:149]
	v_cvt_pk_bf16_f32 v130, v130, v131
	v_cvt_pk_bf16_f32 v131, v132, v133
	v_cvt_pk_bf16_f32 v132, v134, v135
	s_nop 0
	v_cvt_pk_bf16_f32 v133, v136, v137
	global_store_dwordx4 v[162:163], v[130:133], off offset:256 sc1
